# P7 epilogue v2: two rows of rstd per lane + permlane broadcast, packed f32 scale; NSA task OCMP loads hoisted to task prologue
# speedup vs baseline: 1.0200x; 1.0002x over previous
; #define NSA_FINAL(gate_) do { const float lt_ = half_sum(st.l); const float inv_ = lt_ > 0.f ? (gate_) / lt_ : 0.f; \
;         _Pragma("unroll") for (int r = 0; r < 16; ++r) { y0[r] += st.o0[r] * inv_; y1[r] += st.o1[r] * inv_; } fs_reset(st); } while (0)
; DI void nsa_task(LAS unsigned char* lds, const bf16_t* Z, const unsigned* selm, const bf16_t* OCMP, bf16_t* YA, int b, int hk, int c, int tid, int wave, int lane) {
;     ...
;     if (nwin > 0) NSA_FINAL(g_win); else if (nsel > 0) NSA_FINAL(g_slc);
;     if (EN_CMP) {
;         const bf16_t* oc = OCMP + grow * 512 + head * 64;
; #pragma unroll
;         for (int mm = 0; mm < 4; ++mm) {
;             const u32x2 w0 = *(const u32x2*)(oc + 8 * mm + 4 * h), w1 = *(const u32x2*)(oc + 32 + 8 * mm + 4 * h);
;             y0[4 * mm] += g_cmp * bflo(w0.x); y0[4 * mm + 1] += g_cmp * bfhi(w0.x); y0[4 * mm + 2] += g_cmp * bflo(w0.y); y0[4 * mm + 3] += g_cmp * bfhi(w0.y);
;             y1[4 * mm] += g_cmp * bflo(w1.x); y1[4 * mm + 1] += g_cmp * bfhi(w1.x); y1[4 * mm + 2] += g_cmp * bflo(w1.y); y1[4 * mm + 3] += g_cmp * bfhi(w1.y);
;         }
;     }
;     store_y(YA + grow * 1024 + head * 64, y0, y1, h);
.LBB0_712:
	v_lshlrev_b64 v[4:5], 10, v[188:189]
	v_lshl_add_u64 v[4:5], s[18:19], 0, v[4:5]
	v_lshlrev_b32_e32 v2, 1, v195
	v_lshl_add_u64 v[4:5], v[4:5], 0, v[2:3]
	v_lshlrev_b32_e32 v6, 1, v194
	v_mov_b32_e32 v7, v3
	v_lshl_add_u64 v[4:5], v[4:5], 0, v[6:7]
	v_mov_b64_e32 v[8:9], v[226:227]
	v_mov_b64_e32 v[10:11], v[228:229]
	v_mov_b64_e32 v[12:13], v[230:231]
	v_mov_b64_e32 v[14:15], v[232:233]
	v_mov_b64_e32 v[16:17], v[234:235]
	v_mov_b64_e32 v[82:83], v[236:237]
	v_mov_b64_e32 v[84:85], v[238:239]
	s_waitcnt vmcnt(9)
	v_lshlrev_b32_e32 v86, 16, v191
	v_mov_b64_e32 v[4:5], v[240:241]
	v_mul_f32_e32 v86, 0xbfb8aa3b, v86
	v_exp_f32_e32 v86, v86
	v_lshlrev_b32_e32 v87, 16, v187
	ds_bpermute_b32 v88, v215, v214
	v_mul_f32_e32 v87, 0xbfb8aa3b, v87
	v_add_f32_e32 v86, 1.0, v86
	v_exp_f32_e32 v87, v87
	v_rcp_f32_e32 v89, v86
	s_waitcnt lgkmcnt(0)
	v_add_f32_e32 v88, v214, v88
	v_add_f32_e32 v86, 1.0, v87
	v_div_scale_f32 v87, s[4:5], v88, v88, v89
	v_rcp_f32_e32 v90, v87
	v_div_scale_f32 v91, vcc, v89, v88, v89
	v_rcp_f32_e32 v86, v86
	v_fma_f32 v92, -v87, v90, 1.0
	v_fmac_f32_e32 v90, v92, v90
	v_mul_f32_e32 v92, v91, v90
	v_fma_f32 v93, -v87, v92, v91
	v_fmac_f32_e32 v92, v93, v90
	v_fma_f32 v87, -v87, v92, v91
	v_div_fmas_f32 v87, v87, v90, v92
	v_div_fixup_f32 v87, v87, v88, v89
	v_cmp_lt_f32_e32 vcc, 0, v88
	s_nop 1
	v_cndmask_b32_e32 v88, 0, v87, vcc
	v_pk_fma_f32 v[36:37], v[68:69], v[88:89], v[36:37] op_sel_hi:[1,0,1]
	v_pk_fma_f32 v[18:19], v[50:51], v[88:89], v[18:19] op_sel_hi:[1,0,1]
	v_pk_fma_f32 v[20:21], v[52:53], v[88:89], v[20:21] op_sel_hi:[1,0,1]
	v_pk_fma_f32 v[38:39], v[70:71], v[88:89], v[38:39] op_sel_hi:[1,0,1]
	v_pk_fma_f32 v[22:23], v[54:55], v[88:89], v[22:23] op_sel_hi:[1,0,1]
	v_pk_fma_f32 v[28:29], v[60:61], v[88:89], v[28:29] op_sel_hi:[1,0,1]
	v_pk_fma_f32 v[40:41], v[72:73], v[88:89], v[40:41] op_sel_hi:[1,0,1]
	v_pk_fma_f32 v[32:33], v[64:65], v[88:89], v[32:33] op_sel_hi:[1,0,1]
	v_pk_fma_f32 v[34:35], v[66:67], v[88:89], v[34:35] op_sel_hi:[1,0,1]
	v_pk_fma_f32 v[24:25], v[56:57], v[88:89], v[24:25] op_sel_hi:[1,0,1]
	v_pk_fma_f32 v[42:43], v[74:75], v[88:89], v[42:43] op_sel_hi:[1,0,1]
	v_pk_fma_f32 v[44:45], v[76:77], v[88:89], v[44:45] op_sel_hi:[1,0,1]
	v_pk_fma_f32 v[26:27], v[58:59], v[88:89], v[26:27] op_sel_hi:[1,0,1]
	v_pk_fma_f32 v[30:31], v[62:63], v[88:89], v[30:31] op_sel_hi:[1,0,1]
	s_waitcnt vmcnt(7)
	v_lshlrev_b32_e32 v50, 16, v8
	v_and_b32_e32 v51, 0xffff0000, v8
	v_lshlrev_b32_e32 v8, 16, v9
	v_and_b32_e32 v9, 0xffff0000, v9
	s_waitcnt vmcnt(6)
	v_lshlrev_b32_e32 v52, 16, v10
	v_and_b32_e32 v53, 0xffff0000, v10
	v_lshlrev_b32_e32 v10, 16, v11
	v_and_b32_e32 v11, 0xffff0000, v11
	s_waitcnt vmcnt(5)
	v_lshlrev_b32_e32 v54, 16, v12
	v_and_b32_e32 v55, 0xffff0000, v12
	v_pk_fma_f32 v[8:9], v[86:87], v[8:9], v[36:37] op_sel_hi:[0,1,1]
	s_waitcnt vmcnt(2)
	v_lshlrev_b32_e32 v36, 16, v83
	v_and_b32_e32 v37, 0xffff0000, v83
	v_lshlrev_b32_e32 v12, 16, v13
	v_and_b32_e32 v13, 0xffff0000, v13
	v_pk_fma_f32 v[10:11], v[86:87], v[10:11], v[20:21] op_sel_hi:[0,1,1]
	v_pk_fma_f32 v[20:21], v[86:87], v[54:55], v[38:39] op_sel_hi:[0,1,1]
	v_pk_fma_f32 v[28:29], v[86:87], v[36:37], v[28:29] op_sel_hi:[0,1,1]
	v_pk_fma_f32 v[36:37], v[78:79], v[88:89], v[46:47] op_sel_hi:[1,0,1]
	s_waitcnt vmcnt(1)
	v_lshlrev_b32_e32 v38, 16, v84
	v_and_b32_e32 v39, 0xffff0000, v84
	v_pk_fma_f32 v[12:13], v[86:87], v[12:13], v[40:41] op_sel_hi:[0,1,1]
	v_pk_fma_f32 v[36:37], v[86:87], v[38:39], v[36:37] op_sel_hi:[0,1,1]
	v_pk_fma_f32 v[38:39], v[80:81], v[88:89], v[48:49] op_sel_hi:[1,0,1]
	v_lshlrev_b32_e32 v40, 16, v85
	v_and_b32_e32 v41, 0xffff0000, v85
	v_pk_fma_f32 v[38:39], v[86:87], v[40:41], v[38:39] op_sel_hi:[0,1,1]
	s_waitcnt vmcnt(0)
	v_lshlrev_b32_e32 v40, 16, v4
	v_and_b32_e32 v41, 0xffff0000, v4
	v_lshlrev_b32_e32 v4, 16, v5
	v_and_b32_e32 v5, 0xffff0000, v5
	v_pk_fma_f32 v[4:5], v[86:87], v[4:5], v[32:33] op_sel_hi:[0,1,1]
	v_lshlrev_b64 v[32:33], 11, v[188:189]
	v_lshl_add_u64 v[32:33], s[14:15], 0, v[32:33]
	v_pk_fma_f32 v[34:35], v[86:87], v[50:51], v[34:35] op_sel_hi:[0,1,1]
	v_pk_fma_f32 v[18:19], v[86:87], v[52:53], v[18:19] op_sel_hi:[0,1,1]
	v_lshl_add_u64 v[32:33], v[32:33], 0, v[2:3]
	v_lshlrev_b32_e32 v56, 16, v14
	v_and_b32_e32 v57, 0xffff0000, v14
	v_lshlrev_b32_e32 v14, 16, v15
	v_and_b32_e32 v15, 0xffff0000, v15
	v_lshlrev_b32_e32 v58, 16, v16
	v_and_b32_e32 v59, 0xffff0000, v16
	v_lshlrev_b32_e32 v16, 16, v17
	v_and_b32_e32 v17, 0xffff0000, v17
	v_lshl_add_u64 v[6:7], v[32:33], 0, v[6:7]
	v_cvt_pk_bf16_f32 v32, v34, v35
	v_cvt_pk_bf16_f32 v33, v8, v9
	v_cvt_pk_bf16_f32 v8, v18, v19
	v_cvt_pk_bf16_f32 v9, v10, v11
	v_lshlrev_b32_e32 v66, 16, v82
	v_and_b32_e32 v67, 0xffff0000, v82
	v_pk_fma_f32 v[22:23], v[86:87], v[56:57], v[22:23] op_sel_hi:[0,1,1]
	v_pk_fma_f32 v[14:15], v[86:87], v[14:15], v[24:25] op_sel_hi:[0,1,1]
	v_pk_fma_f32 v[24:25], v[86:87], v[58:59], v[42:43] op_sel_hi:[0,1,1]
	v_pk_fma_f32 v[16:17], v[86:87], v[16:17], v[44:45] op_sel_hi:[0,1,1]
	global_store_dwordx2 v[6:7], v[32:33], off
	global_store_dwordx2 v[6:7], v[8:9], off offset:64
	v_cvt_pk_bf16_f32 v8, v20, v21
	v_cvt_pk_bf16_f32 v9, v12, v13
	v_pk_fma_f32 v[26:27], v[86:87], v[66:67], v[26:27] op_sel_hi:[0,1,1]
	v_cvt_pk_bf16_f32 v10, v22, v23
	v_cvt_pk_bf16_f32 v11, v14, v15
	global_store_dwordx2 v[6:7], v[8:9], off offset:16
	global_store_dwordx2 v[6:7], v[10:11], off offset:80
	v_cvt_pk_bf16_f32 v8, v24, v25
	v_cvt_pk_bf16_f32 v9, v16, v17
	v_pk_fma_f32 v[30:31], v[86:87], v[40:41], v[30:31] op_sel_hi:[0,1,1]
	v_cvt_pk_bf16_f32 v10, v26, v27
	v_cvt_pk_bf16_f32 v11, v28, v29
	global_store_dwordx2 v[6:7], v[8:9], off offset:32
	global_store_dwordx2 v[6:7], v[10:11], off offset:96
	v_cvt_pk_bf16_f32 v8, v36, v37
	v_cvt_pk_bf16_f32 v9, v38, v39
	v_cvt_pk_bf16_f32 v10, v30, v31
	v_cvt_pk_bf16_f32 v11, v4, v5
	global_store_dwordx2 v[6:7], v[8:9], off offset:48
	global_store_dwordx2 v[6:7], v[10:11], off offset:112
	s_barrier

; DI float sigmoidf_(float x) { return __builtin_amdgcn_rcpf(1.0f + __expf(-x)); }
; DI void fs_reset(FState& st) { st.o0 = f16zero(); st.o1 = f16zero(); st.m = NINF; st.l = 0.f; }
; DI void nsa_task(LAS unsigned char* lds, const bf16_t* Z, const unsigned* selm, const bf16_t* OCMP, bf16_t* YA, int b, int hk, int c, int tid, int wave, int lane) {
;     ...
;     const float g_cmp = sigmoidf_(bf2f(zr[ZC_GA + head])), g_slc = sigmoidf_(bf2f(zr[ZC_GA + 8 + head])), g_win = sigmoidf_(bf2f(zr[ZC_GA + 16 + head]));
;     f32x16 y0 = f16zero(), y1 = f16zero();
;     FState st; fs_reset(st);
;     const int nsel = EN_SLC ? c + 1 : 0, nwin = EN_WIN ? (c + 1 < 9 ? c + 1 : 9) : 0, ntot = nsel + nwin;
;     const int skey = tid >> 3, sch = tid & 7;
;     const int kdst = skey * 128 + ((sch ^ ((skey >> 1) & 7)) << 4), vdst = 8192 + skey * 128 + ((sch * 16) ^ (((skey >> 1) & 1) << 6));
;     const bf16_t* sbase = Z + ((size_t)b * SEQ + skey) * NZ + hk * 64 + sch * 8;
;     u32x4 kA = {0u, 0u, 0u, 0u}, vA = kA, kB = kA, vB = kA, kC = kA, vC = kA;
;     ...
;         const bf16_t* oc = OCMP + grow * 512 + head * 64;
; #pragma unroll
;         for (int mm = 0; mm < 4; ++mm) {
;             const u32x2 w0 = *(const u32x2*)(oc + 8 * mm + 4 * h), w1 = *(const u32x2*)(oc + 32 + 8 * mm + 4 * h);
.LBB0_740:
	s_waitcnt vmcnt(3)
	v_lshlrev_b32_e32 v5, 16, v5
	v_mul_f32_e32 v5, 0xbfb8aa3b, v5
	v_exp_f32_e32 v5, v5
	v_lshlrev_b32_e32 v195, 6, v4
	v_lshlrev_b32_e32 v4, 7, v194
	v_lshlrev_b32_e32 v6, 4, v205
	v_add_f32_e32 v5, 1.0, v5
	v_rcp_f32_e32 v197, v5
	v_lshlrev_b32_e32 v5, 6, v206
	v_and_b32_e32 v5, 64, v5
	v_mov_b32_e32 v16, v3
	v_mov_b32_e32 v17, v3
	v_and_or_b32 v205, v6, s66, v4
	v_lshlrev_b32_e32 v206, 4, v207
	v_lshlrev_b32_e32 v207, 4, v208
	v_lshlrev_b32_e32 v208, 4, v209
	v_lshlrev_b32_e32 v209, 4, v212
	s_add_i32 s4, s50, s69
	v_bitop3_b32 v212, v5, v4, v2 bitop3:0xde
	v_mov_b32_e32 v2, v3
	v_mov_b32_e32 v4, v3
	v_mov_b32_e32 v5, v3
	v_mov_b32_e32 v6, v3
	v_mov_b32_e32 v7, v3
	v_mov_b32_e32 v8, v3
	v_mov_b32_e32 v9, v3
	v_mov_b32_e32 v10, v3
	v_mov_b32_e32 v11, v3
	v_mov_b32_e32 v12, v3
	v_mov_b32_e32 v13, v3
	v_mov_b32_e32 v14, v3
	v_mov_b32_e32 v15, v3
	v_mov_b64_e32 v[80:81], v[16:17]
	v_mov_b64_e32 v[64:65], v[16:17]
	v_mov_b64_e32 v[48:49], v[16:17]
	v_mov_b64_e32 v[32:33], v[16:17]
	v_lshlrev_b32_e32 v194, 2, v210
	v_add_u32_e32 v210, 0xfffffe00, v190
	v_lshlrev_b32_e32 v211, 7, v211
	s_add_i32 s52, s4, -5
	s_mov_b32 s53, 0
	v_sub_u32_e32 v213, 0, v202
	s_sub_i32 s70, 0, s69
	s_add_i32 s71, s69, -2
	s_add_i32 s72, s69, -1
	v_mov_b32_e32 v214, 0
	v_mov_b32_e32 v216, 0xff800000
	s_mov_b32 s74, 0
	v_mov_b64_e32 v[78:79], v[14:15]
	v_mov_b64_e32 v[76:77], v[12:13]
	v_mov_b64_e32 v[74:75], v[10:11]
	v_mov_b64_e32 v[72:73], v[8:9]
	v_mov_b64_e32 v[70:71], v[6:7]
	v_mov_b64_e32 v[68:69], v[4:5]
	v_mov_b64_e32 v[66:67], v[2:3]
	v_mov_b64_e32 v[62:63], v[14:15]
	v_mov_b64_e32 v[60:61], v[12:13]
	v_mov_b64_e32 v[58:59], v[10:11]
	v_mov_b64_e32 v[56:57], v[8:9]
	v_mov_b64_e32 v[54:55], v[6:7]
	v_mov_b64_e32 v[52:53], v[4:5]
	v_mov_b64_e32 v[50:51], v[2:3]
	v_mov_b64_e32 v[46:47], v[14:15]
	v_mov_b64_e32 v[44:45], v[12:13]
	v_mov_b64_e32 v[42:43], v[10:11]
	v_mov_b64_e32 v[40:41], v[8:9]
	v_mov_b64_e32 v[38:39], v[6:7]
	v_mov_b64_e32 v[36:37], v[4:5]
	v_mov_b64_e32 v[34:35], v[2:3]
	v_mov_b64_e32 v[30:31], v[14:15]
	v_mov_b64_e32 v[28:29], v[12:13]
	v_mov_b64_e32 v[26:27], v[10:11]
	v_mov_b64_e32 v[24:25], v[8:9]
	v_mov_b64_e32 v[22:23], v[6:7]
	v_mov_b64_e32 v[20:21], v[4:5]
	v_mov_b64_e32 v[18:19], v[2:3]
	v_lshlrev_b64 v[242:243], 10, v[188:189]
	v_lshl_add_u64 v[242:243], s[18:19], 0, v[242:243]
	v_lshlrev_b32_e32 v244, 1, v195
	v_mov_b32_e32 v245, 0
	v_lshl_add_u64 v[242:243], v[242:243], 0, v[244:245]
	v_lshlrev_b32_e32 v244, 1, v194
	v_lshl_add_u64 v[242:243], v[242:243], 0, v[244:245]
	global_load_dwordx2 v[226:227], v[242:243], off
	global_load_dwordx2 v[228:229], v[242:243], off offset:64
	global_load_dwordx2 v[230:231], v[242:243], off offset:16
	global_load_dwordx2 v[232:233], v[242:243], off offset:80
	global_load_dwordx2 v[234:235], v[242:243], off offset:32
	global_load_dwordx2 v[236:237], v[242:243], off offset:96
	global_load_dwordx2 v[238:239], v[242:243], off offset:48
	global_load_dwordx2 v[240:241], v[242:243], off offset:112

.LBB0_1034:
	ds_read_b128 v[146:149], v156
	ds_read_b128 v[150:153], v156 offset:1024
	ds_read_b128 v[162:165], v156 offset:2048
	ds_read_b128 v[166:169], v156 offset:3072
	ds_read_b128 v[170:173], v157
	ds_read_b128 v[174:177], v157 offset:1024
	ds_read_b128 v[178:181], v157 offset:2048
	ds_read_b128 v[182:185], v157 offset:3072
	s_add_u32 s42, s40, 0xfffc0080
	s_addc_u32 s43, s41, -1
	s_cmp_eq_u32 s63, 12
	s_cselect_b32 s45, s29, s43
	s_cselect_b32 s44, s59, s42
	s_cselect_b32 s43, s27, s62
	s_cselect_b32 s42, s60, s61
	v_lshl_add_u64 v[220:221], s[40:41], 0, v[138:139]
	s_add_i32 m0, s48, 0xc000
	ds_read_b128 v[186:189], v158
	ds_read_b128 v[190:193], v158 offset:1024
	ds_read_b128 v[194:197], v158 offset:2048
	ds_read_b128 v[200:203], v158 offset:3072
	ds_read_b128 v[204:207], v158 offset:4096
	ds_read_b128 v[208:211], v158 offset:5120
	ds_read_b128 v[212:215], v158 offset:6144
	ds_read_b128 v[216:219], v158 offset:7168
	global_load_lds_dwordx4 v[220:221], off
	v_lshl_add_u64 v[220:221], s[40:41], 0, v[140:141]
	s_add_i32 m0, s48, 0xe000
	s_nop 0
	global_load_lds_dwordx4 v[220:221], off
	s_waitcnt vmcnt(8)
	s_waitcnt lgkmcnt(0)
	s_barrier
	s_setprio 1
	s_waitcnt lgkmcnt(0)
	v_mfma_f32_16x16x32_bf16 v[126:129], v[146:149], v[186:189], v[126:129]
	v_mfma_f32_16x16x32_bf16 v[122:125], v[162:165], v[186:189], v[122:125]
	v_mfma_f32_16x16x32_bf16 v[110:113], v[146:149], v[194:197], v[110:113]
	v_mfma_f32_16x16x32_bf16 v[106:109], v[162:165], v[194:197], v[106:109]
	v_mfma_f32_16x16x32_bf16 v[94:97], v[146:149], v[204:207], v[94:97]
	v_mfma_f32_16x16x32_bf16 v[90:93], v[162:165], v[204:207], v[90:93]
	v_mfma_f32_16x16x32_bf16 v[78:81], v[146:149], v[212:215], v[78:81]
	v_mfma_f32_16x16x32_bf16 v[74:77], v[162:165], v[212:215], v[74:77]
	v_mfma_f32_16x16x32_bf16 v[126:129], v[150:153], v[190:193], v[126:129]
	v_mfma_f32_16x16x32_bf16 v[122:125], v[166:169], v[190:193], v[122:125]
	v_mfma_f32_16x16x32_bf16 v[110:113], v[150:153], v[200:203], v[110:113]
	v_mfma_f32_16x16x32_bf16 v[106:109], v[166:169], v[200:203], v[106:109]
	v_mfma_f32_16x16x32_bf16 v[94:97], v[150:153], v[208:211], v[94:97]
	v_mfma_f32_16x16x32_bf16 v[90:93], v[166:169], v[208:211], v[90:93]
	v_mfma_f32_16x16x32_bf16 v[78:81], v[150:153], v[216:219], v[78:81]
	v_mfma_f32_16x16x32_bf16 v[74:77], v[166:169], v[216:219], v[74:77]
	s_setprio 0
	s_setprio 1
	v_mfma_f32_16x16x32_bf16 v[118:121], v[170:173], v[186:189], v[118:121]
	v_mfma_f32_16x16x32_bf16 v[114:117], v[178:181], v[186:189], v[114:117]
	v_mfma_f32_16x16x32_bf16 v[102:105], v[170:173], v[194:197], v[102:105]
	v_mfma_f32_16x16x32_bf16 v[98:101], v[178:181], v[194:197], v[98:101]
	v_mfma_f32_16x16x32_bf16 v[86:89], v[170:173], v[204:207], v[86:89]
	v_mfma_f32_16x16x32_bf16 v[82:85], v[178:181], v[204:207], v[82:85]
	v_mfma_f32_16x16x32_bf16 v[70:73], v[170:173], v[212:215], v[70:73]
	v_mfma_f32_16x16x32_bf16 v[66:69], v[178:181], v[212:215], v[66:69]
	v_mfma_f32_16x16x32_bf16 v[118:121], v[174:177], v[190:193], v[118:121]
	v_mfma_f32_16x16x32_bf16 v[114:117], v[182:185], v[190:193], v[114:117]
	v_mfma_f32_16x16x32_bf16 v[102:105], v[174:177], v[200:203], v[102:105]
	v_mfma_f32_16x16x32_bf16 v[98:101], v[182:185], v[200:203], v[98:101]
	v_mfma_f32_16x16x32_bf16 v[86:89], v[174:177], v[208:211], v[86:89]
	v_mfma_f32_16x16x32_bf16 v[82:85], v[182:185], v[208:211], v[82:85]
	v_mfma_f32_16x16x32_bf16 v[70:73], v[174:177], v[216:219], v[70:73]
	v_mfma_f32_16x16x32_bf16 v[66:69], v[182:185], v[216:219], v[66:69]
	s_setprio 0
	s_barrier
	s_add_i32 s64, s55, s46
	v_lshl_add_u64 v[220:221], s[42:43], 0, v[134:135]
	s_mov_b32 m0, s64
	ds_read_b128 v[186:189], v158 offset:16384
	ds_read_b128 v[190:193], v158 offset:17408
	ds_read_b128 v[194:197], v158 offset:18432
	ds_read_b128 v[200:203], v158 offset:19456
	ds_read_b128 v[204:207], v158 offset:20480
	ds_read_b128 v[208:211], v158 offset:21504
	ds_read_b128 v[212:215], v158 offset:22528
	ds_read_b128 v[216:219], v158 offset:23552
	global_load_lds_dwordx4 v[220:221], off
	s_add_i32 m0, s64, 0x2000
	s_add_u32 s64, s42, 0x40000
	v_lshl_add_u64 v[222:223], s[42:43], 0, v[130:131]
	s_addc_u32 s65, s43, 0
	s_add_i32 s66, s56, s46
	global_load_lds_dwordx4 v[222:223], off
	v_lshl_add_u64 v[224:225], s[64:65], 0, v[134:135]
	s_mov_b32 m0, s66
	v_lshl_add_u64 v[226:227], s[44:45], 0, v[132:133]
	global_load_lds_dwordx4 v[224:225], off
	v_lshl_add_u64 v[224:225], s[64:65], 0, v[130:131]
	s_add_i32 m0, s66, 0x2000
	s_nop 0
	global_load_lds_dwordx4 v[224:225], off
	v_lshl_add_u64 v[224:225], s[44:45], 0, v[136:137]
	s_mov_b32 m0, s48
	s_nop 0
	global_load_lds_dwordx4 v[224:225], off
	s_mov_b32 m0, s49
	s_nop 0
	global_load_lds_dwordx4 v[226:227], off
	s_waitcnt vmcnt(8)
	s_waitcnt lgkmcnt(0)
	s_barrier
	s_setprio 1
	s_waitcnt lgkmcnt(0)
	v_mfma_f32_16x16x32_bf16 v[62:65], v[146:149], v[186:189], v[62:65]
	v_mfma_f32_16x16x32_bf16 v[58:61], v[162:165], v[186:189], v[58:61]
	v_mfma_f32_16x16x32_bf16 v[46:49], v[146:149], v[194:197], v[46:49]
	v_mfma_f32_16x16x32_bf16 v[42:45], v[162:165], v[194:197], v[42:45]
	v_mfma_f32_16x16x32_bf16 v[30:33], v[146:149], v[204:207], v[30:33]
	v_mfma_f32_16x16x32_bf16 v[26:29], v[162:165], v[204:207], v[26:29]
	v_mfma_f32_16x16x32_bf16 v[14:17], v[146:149], v[212:215], v[14:17]
	v_mfma_f32_16x16x32_bf16 v[10:13], v[162:165], v[212:215], v[10:13]
	v_mfma_f32_16x16x32_bf16 v[62:65], v[150:153], v[190:193], v[62:65]
	v_mfma_f32_16x16x32_bf16 v[58:61], v[166:169], v[190:193], v[58:61]
	v_mfma_f32_16x16x32_bf16 v[46:49], v[150:153], v[200:203], v[46:49]
	v_mfma_f32_16x16x32_bf16 v[42:45], v[166:169], v[200:203], v[42:45]
	v_mfma_f32_16x16x32_bf16 v[30:33], v[150:153], v[208:211], v[30:33]
	v_mfma_f32_16x16x32_bf16 v[26:29], v[166:169], v[208:211], v[26:29]
	v_mfma_f32_16x16x32_bf16 v[14:17], v[150:153], v[216:219], v[14:17]
	v_mfma_f32_16x16x32_bf16 v[10:13], v[166:169], v[216:219], v[10:13]
	s_setprio 0
	s_setprio 1
	v_mfma_f32_16x16x32_bf16 v[54:57], v[170:173], v[186:189], v[54:57]
	v_mfma_f32_16x16x32_bf16 v[50:53], v[178:181], v[186:189], v[50:53]
	v_mfma_f32_16x16x32_bf16 v[38:41], v[170:173], v[194:197], v[38:41]
	v_mfma_f32_16x16x32_bf16 v[34:37], v[178:181], v[194:197], v[34:37]
	v_mfma_f32_16x16x32_bf16 v[22:25], v[170:173], v[204:207], v[22:25]
	v_mfma_f32_16x16x32_bf16 v[18:21], v[178:181], v[204:207], v[18:21]
	v_mfma_f32_16x16x32_bf16 v[6:9], v[170:173], v[212:215], v[6:9]
	v_mfma_f32_16x16x32_bf16 v[2:5], v[178:181], v[212:215], v[2:5]
	v_mfma_f32_16x16x32_bf16 v[54:57], v[174:177], v[190:193], v[54:57]
	v_mfma_f32_16x16x32_bf16 v[50:53], v[182:185], v[190:193], v[50:53]
	v_mfma_f32_16x16x32_bf16 v[38:41], v[174:177], v[200:203], v[38:41]
	v_mfma_f32_16x16x32_bf16 v[34:37], v[182:185], v[200:203], v[34:37]
	v_mfma_f32_16x16x32_bf16 v[22:25], v[174:177], v[208:211], v[22:25]
	v_mfma_f32_16x16x32_bf16 v[18:21], v[182:185], v[208:211], v[18:21]
	v_mfma_f32_16x16x32_bf16 v[6:9], v[174:177], v[216:219], v[6:9]
	v_mfma_f32_16x16x32_bf16 v[2:5], v[182:185], v[216:219], v[2:5]
	s_setprio 0
	s_barrier
	s_add_i32 s64, 0, 0x18000
	v_add_u32_e32 v161, s64, v154
	s_add_i32 s65, 0, 0x1c000
	ds_read_b128 v[146:149], v161
	ds_read_b128 v[150:153], v161 offset:1024
	ds_read_b128 v[162:165], v161 offset:2048
	ds_read_b128 v[166:169], v161 offset:3072
	v_add_u32_e32 v161, s65, v154
	ds_read_b128 v[170:173], v161
	ds_read_b128 v[174:177], v161 offset:1024
	ds_read_b128 v[178:181], v161 offset:2048
	ds_read_b128 v[182:185], v161 offset:3072
	s_add_u32 s44, s44, 0x40000
	s_addc_u32 s45, s45, 0
	s_mov_b32 m0, s50
	v_lshl_add_u64 v[228:229], s[44:45], 0, v[136:137]
	ds_read_b128 v[186:189], v158 offset:32768
	ds_read_b128 v[190:193], v158 offset:33792
	ds_read_b128 v[194:197], v158 offset:34816
	ds_read_b128 v[200:203], v158 offset:35840
	ds_read_b128 v[204:207], v158 offset:36864
	ds_read_b128 v[208:211], v158 offset:37888
	ds_read_b128 v[212:215], v158 offset:38912
	ds_read_b128 v[216:219], v158 offset:39936
	global_load_lds_dwordx4 v[228:229], off
	v_lshl_add_u64 v[228:229], s[44:45], 0, v[132:133]
	s_mov_b32 m0, s51
	s_nop 0
	global_load_lds_dwordx4 v[228:229], off
	s_waitcnt vmcnt(8)
	s_waitcnt lgkmcnt(0)
	s_barrier
	s_setprio 1
	s_waitcnt lgkmcnt(0)
	v_mfma_f32_16x16x32_bf16 v[126:129], v[146:149], v[186:189], v[126:129]
	v_mfma_f32_16x16x32_bf16 v[122:125], v[162:165], v[186:189], v[122:125]
	v_mfma_f32_16x16x32_bf16 v[110:113], v[146:149], v[194:197], v[110:113]
	v_mfma_f32_16x16x32_bf16 v[106:109], v[162:165], v[194:197], v[106:109]
	v_mfma_f32_16x16x32_bf16 v[94:97], v[146:149], v[204:207], v[94:97]
	v_mfma_f32_16x16x32_bf16 v[90:93], v[162:165], v[204:207], v[90:93]
	v_mfma_f32_16x16x32_bf16 v[78:81], v[146:149], v[212:215], v[78:81]
	v_mfma_f32_16x16x32_bf16 v[74:77], v[162:165], v[212:215], v[74:77]
	v_mfma_f32_16x16x32_bf16 v[126:129], v[150:153], v[190:193], v[126:129]
	v_mfma_f32_16x16x32_bf16 v[122:125], v[166:169], v[190:193], v[122:125]
	v_mfma_f32_16x16x32_bf16 v[110:113], v[150:153], v[200:203], v[110:113]
	v_mfma_f32_16x16x32_bf16 v[106:109], v[166:169], v[200:203], v[106:109]
	v_mfma_f32_16x16x32_bf16 v[94:97], v[150:153], v[208:211], v[94:97]
	v_mfma_f32_16x16x32_bf16 v[90:93], v[166:169], v[208:211], v[90:93]
	v_mfma_f32_16x16x32_bf16 v[78:81], v[150:153], v[216:219], v[78:81]
	v_mfma_f32_16x16x32_bf16 v[74:77], v[166:169], v[216:219], v[74:77]
	s_setprio 0
	s_setprio 1
	v_mfma_f32_16x16x32_bf16 v[118:121], v[170:173], v[186:189], v[118:121]
	v_mfma_f32_16x16x32_bf16 v[114:117], v[178:181], v[186:189], v[114:117]
	v_mfma_f32_16x16x32_bf16 v[102:105], v[170:173], v[194:197], v[102:105]
	v_mfma_f32_16x16x32_bf16 v[98:101], v[178:181], v[194:197], v[98:101]
	v_mfma_f32_16x16x32_bf16 v[86:89], v[170:173], v[204:207], v[86:89]
	v_mfma_f32_16x16x32_bf16 v[82:85], v[178:181], v[204:207], v[82:85]
	v_mfma_f32_16x16x32_bf16 v[70:73], v[170:173], v[212:215], v[70:73]
	v_mfma_f32_16x16x32_bf16 v[66:69], v[178:181], v[212:215], v[66:69]
	v_mfma_f32_16x16x32_bf16 v[118:121], v[174:177], v[190:193], v[118:121]
	v_mfma_f32_16x16x32_bf16 v[114:117], v[182:185], v[190:193], v[114:117]
	v_mfma_f32_16x16x32_bf16 v[102:105], v[174:177], v[200:203], v[102:105]
	v_mfma_f32_16x16x32_bf16 v[98:101], v[182:185], v[200:203], v[98:101]
	v_mfma_f32_16x16x32_bf16 v[86:89], v[174:177], v[208:211], v[86:89]
	v_mfma_f32_16x16x32_bf16 v[82:85], v[182:185], v[208:211], v[82:85]
	v_mfma_f32_16x16x32_bf16 v[70:73], v[174:177], v[216:219], v[70:73]
	v_mfma_f32_16x16x32_bf16 v[66:69], v[182:185], v[216:219], v[66:69]
	s_setprio 0
	s_barrier
;     DI void operator()(const Acc& acc, const Unit& u, int wr, int wc, int fr, int fq) const {
;         const int row0 = u.pm * 256 + wr * 64 + fr;
; #pragma unroll
;         for (int ai = 0; ai < 2; ++ai)
; #pragma unroll
;             for (int m = 0; m < 4; ++m) {
;                 const int r = row0 + ai * 128 + m * 16;
;                 const f32x4* sp = (const f32x4*)(SS + (size_t)r * 16);
;                 const f32x4 s0 = sp[0], s1 = sp[1], s2 = sp[2], s3 = sp[3];
;                 const float tot = ((s0[0] + s0[1]) + (s0[2] + s0[3])) + ((s1[0] + s1[1]) + (s1[2] + s1[3])) + ((s2[0] + s2[1]) + (s2[2] + s2[3])) + ((s3[0] + s3[1]) + (s3[2] + s3[3]));
;                 const float rr = 1.0f / sqrtf(tot * (1.0f / DM) + EPS);
	s_add_i32 s44, s64, s46
	v_lshl_add_u64 v[220:221], v[220:221], 0, s[16:17]
	s_mov_b32 m0, s44
	ds_read_b128 v[186:189], v158 offset:49152
	ds_read_b128 v[190:193], v158 offset:50176
	ds_read_b128 v[194:197], v158 offset:51200
	ds_read_b128 v[200:203], v158 offset:52224
	ds_read_b128 v[204:207], v158 offset:53248
	ds_read_b128 v[208:211], v158 offset:54272
	ds_read_b128 v[212:215], v158 offset:55296
	ds_read_b128 v[216:219], v158 offset:56320
	global_load_lds_dwordx4 v[220:221], off
	s_add_i32 m0, s44, 0x2000
	s_add_u32 s42, s42, 0x40080
	v_lshl_add_u64 v[220:221], v[222:223], 0, s[16:17]
	s_addc_u32 s43, s43, 0
	s_add_i32 s44, s65, s46
	global_load_lds_dwordx4 v[220:221], off
	v_lshl_add_u64 v[220:221], s[42:43], 0, v[134:135]
	s_mov_b32 m0, s44
	s_nop 0
	global_load_lds_dwordx4 v[220:221], off
	v_lshl_add_u64 v[220:221], s[42:43], 0, v[130:131]
	s_add_i32 m0, s44, 0x2000
	s_nop 0
	global_load_lds_dwordx4 v[220:221], off
	v_lshl_add_u64 v[220:221], v[224:225], 0, s[16:17]
	s_mov_b32 m0, s53
	s_nop 0
	global_load_lds_dwordx4 v[220:221], off
	v_lshl_add_u64 v[220:221], v[226:227], 0, s[16:17]
	s_mov_b32 m0, s54
	s_nop 0
	global_load_lds_dwordx4 v[220:221], off
	s_waitcnt vmcnt(8)
	s_waitcnt lgkmcnt(0)
	s_barrier
	s_setprio 1
	s_waitcnt lgkmcnt(0)
	v_mfma_f32_16x16x32_bf16 v[62:65], v[146:149], v[186:189], v[62:65]
	v_mfma_f32_16x16x32_bf16 v[58:61], v[162:165], v[186:189], v[58:61]
	v_mfma_f32_16x16x32_bf16 v[46:49], v[146:149], v[194:197], v[46:49]
	v_mfma_f32_16x16x32_bf16 v[42:45], v[162:165], v[194:197], v[42:45]
	v_mfma_f32_16x16x32_bf16 v[30:33], v[146:149], v[204:207], v[30:33]
	v_mfma_f32_16x16x32_bf16 v[26:29], v[162:165], v[204:207], v[26:29]
	v_mfma_f32_16x16x32_bf16 v[14:17], v[146:149], v[212:215], v[14:17]
	v_mfma_f32_16x16x32_bf16 v[10:13], v[162:165], v[212:215], v[10:13]
	v_mfma_f32_16x16x32_bf16 v[62:65], v[150:153], v[190:193], v[62:65]
	v_mfma_f32_16x16x32_bf16 v[58:61], v[166:169], v[190:193], v[58:61]
	v_mfma_f32_16x16x32_bf16 v[46:49], v[150:153], v[200:203], v[46:49]
	v_mfma_f32_16x16x32_bf16 v[42:45], v[166:169], v[200:203], v[42:45]
	v_mfma_f32_16x16x32_bf16 v[30:33], v[150:153], v[208:211], v[30:33]
	v_mfma_f32_16x16x32_bf16 v[26:29], v[166:169], v[208:211], v[26:29]
	v_mfma_f32_16x16x32_bf16 v[14:17], v[150:153], v[216:219], v[14:17]
	v_mfma_f32_16x16x32_bf16 v[10:13], v[166:169], v[216:219], v[10:13]
	s_setprio 0
	s_setprio 1
	v_mfma_f32_16x16x32_bf16 v[54:57], v[170:173], v[186:189], v[54:57]
	v_mfma_f32_16x16x32_bf16 v[50:53], v[178:181], v[186:189], v[50:53]
	v_mfma_f32_16x16x32_bf16 v[38:41], v[170:173], v[194:197], v[38:41]
	v_mfma_f32_16x16x32_bf16 v[34:37], v[178:181], v[194:197], v[34:37]
	v_mfma_f32_16x16x32_bf16 v[22:25], v[170:173], v[204:207], v[22:25]
	v_mfma_f32_16x16x32_bf16 v[18:21], v[178:181], v[204:207], v[18:21]
	v_mfma_f32_16x16x32_bf16 v[6:9], v[170:173], v[212:215], v[6:9]
	v_mfma_f32_16x16x32_bf16 v[2:5], v[178:181], v[212:215], v[2:5]
	v_mfma_f32_16x16x32_bf16 v[54:57], v[174:177], v[190:193], v[54:57]
	v_mfma_f32_16x16x32_bf16 v[50:53], v[182:185], v[190:193], v[50:53]
	v_mfma_f32_16x16x32_bf16 v[38:41], v[174:177], v[200:203], v[38:41]
	v_mfma_f32_16x16x32_bf16 v[34:37], v[182:185], v[200:203], v[34:37]
	v_mfma_f32_16x16x32_bf16 v[22:25], v[174:177], v[208:211], v[22:25]
	v_mfma_f32_16x16x32_bf16 v[18:21], v[182:185], v[208:211], v[18:21]
	v_mfma_f32_16x16x32_bf16 v[6:9], v[174:177], v[216:219], v[6:9]
	v_mfma_f32_16x16x32_bf16 v[2:5], v[182:185], v[216:219], v[2:5]
	s_setprio 0
	s_barrier
	s_add_i32 s63, s63, 2
	s_add_u32 s40, s40, 0x100
	s_addc_u32 s41, s41, 0
	s_add_u32 s61, s61, 0x100
	s_addc_u32 s62, s62, 0
	s_cmp_gt_u32 s63, 13
	s_cbranch_scc0 .LBB0_1034
	v_lshl_add_u32 v150, s6, 8, v1
	v_and_b32_e32 v151, 12, v155
	v_lshlrev_b32_e32 v152, 6, v150
	v_lshl_add_u32 v152, v151, 8, v152
	v_add_u32_e32 v153, 0x2000, v152
	global_load_dwordx4 v[162:165], v152, s[14:15]
	global_load_dwordx4 v[166:169], v152, s[14:15] offset:16
	global_load_dwordx4 v[170:173], v152, s[14:15] offset:32
	global_load_dwordx4 v[174:177], v152, s[14:15] offset:48
	global_load_dwordx4 v[178:181], v153, s[14:15]
	global_load_dwordx4 v[182:185], v153, s[14:15] offset:16
	global_load_dwordx4 v[186:189], v153, s[14:15] offset:32
	global_load_dwordx4 v[190:193], v153, s[14:15] offset:48
	v_lshl_or_b32 v148, s7, 7, v155
	v_lshlrev_b32_e32 v148, 1, v148
	v_mad_u32_u24 v161, v150, s58, v148
	v_mov_b32_e32 v196, 0xbfb8aa3b
	s_and_b64 vcc, exec, s[20:21]
	s_cbranch_vccz .LBB0_1037
	s_barrier
; DI unsigned pk2(float lo, float hi) { const f32x2 v = {lo, hi}; const bf16x2_t b = __builtin_convertvector(v, bf16x2_t); return __builtin_bit_cast(unsigned, b); }
; DI float sigmoidf_(float x) { return __builtin_amdgcn_rcpf(1.0f + __expf(-x)); }
;     DI void operator()(const Acc& acc, const Unit& u, int wr, int wc, int fr, int fq) const {
;     ...
;                 const int r = row0 + ai * 128 + m * 16;
;                 const f32x4* sp = (const f32x4*)(SS + (size_t)r * 16);
;                 const f32x4 s0 = sp[0], s1 = sp[1], s2 = sp[2], s3 = sp[3];
;                 const float tot = ((s0[0] + s0[1]) + (s0[2] + s0[3])) + ((s1[0] + s1[1]) + (s1[2] + s1[3])) + ((s2[0] + s2[1]) + (s2[2] + s2[3])) + ((s3[0] + s3[1]) + (s3[2] + s3[3]));
;                 const float rr = 1.0f / sqrtf(tot * (1.0f / DM) + EPS);
; #pragma unroll
;                 for (int bj = 0; bj < 2; ++bj) {
;                     const int f0 = u.pn * 128 + bj * 64 + wc * 16 + 4 * fq;
;                     const f32x4 g = acc[ai][bj][m][0] * rr, up = acc[ai][bj][m][1] * rr;
;                     float o[4];
; #pragma unroll
;                     for (int i = 0; i < 4; ++i) o[i] = g[i] * sigmoidf_(g[i]) * up[i];
;                     u32x2 w; w.x = pk2(o[0], o[1]); w.y = pk2(o[2], o[3]);
;                     *(u32x2*)(ACT + (size_t)r * DFF + f0) = w;
.LBB0_1037:
	s_waitcnt vmcnt(0)
	v_add_f32_e32 v162, v162, v163
	v_add_f32_e32 v164, v164, v165
	v_add_f32_e32 v166, v166, v167
	v_add_f32_e32 v168, v168, v169
	v_add_f32_e32 v170, v170, v171
	v_add_f32_e32 v172, v172, v173
	v_add_f32_e32 v174, v174, v175
	v_add_f32_e32 v176, v176, v177
	v_add_f32_e32 v162, v162, v164
	v_add_f32_e32 v166, v166, v168
	v_add_f32_e32 v170, v170, v172
	v_add_f32_e32 v174, v174, v176
	v_add_f32_e32 v178, v178, v179
	v_add_f32_e32 v180, v180, v181
	v_add_f32_e32 v182, v182, v183
	v_add_f32_e32 v184, v184, v185
	v_add_f32_e32 v186, v186, v187
	v_add_f32_e32 v188, v188, v189
	v_add_f32_e32 v190, v190, v191
	v_add_f32_e32 v192, v192, v193
	v_add_f32_e32 v178, v178, v180
	v_add_f32_e32 v182, v182, v184
	v_add_f32_e32 v186, v186, v188
	v_add_f32_e32 v190, v190, v192
	v_add_f32_e32 v162, v162, v166
	v_add_f32_e32 v162, v162, v170
	v_add_f32_e32 v162, v162, v174
	v_add_f32_e32 v178, v178, v182
	v_add_f32_e32 v178, v178, v186
	v_add_f32_e32 v178, v178, v190
	v_fmamk_f32 v204, v162, 0x3a800000, v159
	v_mul_f32_e32 v205, 0x4f800000, v204
	v_cmp_gt_f32_e32 vcc, s57, v204
	s_nop 1
	v_cndmask_b32_e32 v204, v204, v205, vcc
	v_sqrt_f32_e32 v205, v204
	s_nop 0
	v_add_u32_e32 v206, -1, v205
	v_add_u32_e32 v207, 1, v205
	v_fma_f32 v208, -v206, v205, v204
	v_fma_f32 v209, -v207, v205, v204
	v_cmp_ge_f32_e64 s[6:7], 0, v208
	s_nop 1
	v_cndmask_b32_e64 v206, v205, v206, s[6:7]
	v_cmp_lt_f32_e64 s[6:7], 0, v209
	s_nop 1
	v_cndmask_b32_e64 v206, v206, v207, s[6:7]
	v_mul_f32_e32 v205, 0x37800000, v206
	v_cndmask_b32_e32 v206, v206, v205, vcc
	v_cmp_class_f32_e32 vcc, v204, v160
	s_nop 1
	v_cndmask_b32_e32 v204, v206, v204, vcc
	v_div_scale_f32 v206, s[6:7], v204, v204, 1.0
	v_rcp_f32_e32 v205, v206
	v_div_scale_f32 v207, vcc, 1.0, v204, 1.0
	v_fma_f32 v208, -v206, v205, 1.0
	v_fmac_f32_e32 v205, v208, v205
	v_mul_f32_e32 v208, v207, v205
	v_fma_f32 v209, -v206, v208, v207
	v_fmac_f32_e32 v208, v209, v205
	v_fma_f32 v206, -v206, v208, v207
	v_div_fmas_f32 v206, v206, v205, v208
	v_div_fixup_f32 v162, v206, v204, 1.0
	v_fmamk_f32 v204, v178, 0x3a800000, v159
	v_mul_f32_e32 v205, 0x4f800000, v204
	v_cmp_gt_f32_e32 vcc, s57, v204
	s_nop 1
	v_cndmask_b32_e32 v204, v204, v205, vcc
	v_sqrt_f32_e32 v205, v204
	s_nop 0
	v_add_u32_e32 v206, -1, v205
	v_add_u32_e32 v207, 1, v205
	v_fma_f32 v208, -v206, v205, v204
	v_fma_f32 v209, -v207, v205, v204
	v_cmp_ge_f32_e64 s[6:7], 0, v208
	s_nop 1
	v_cndmask_b32_e64 v206, v205, v206, s[6:7]
	v_cmp_lt_f32_e64 s[6:7], 0, v209
	s_nop 1
	v_cndmask_b32_e64 v206, v206, v207, s[6:7]
	v_mul_f32_e32 v205, 0x37800000, v206
	v_cndmask_b32_e32 v206, v206, v205, vcc
	v_cmp_class_f32_e32 vcc, v204, v160
	s_nop 1
	v_cndmask_b32_e32 v204, v206, v204, vcc
	v_div_scale_f32 v206, s[6:7], v204, v204, 1.0
	v_rcp_f32_e32 v205, v206
	v_div_scale_f32 v207, vcc, 1.0, v204, 1.0
	v_fma_f32 v208, -v206, v205, 1.0
	v_fmac_f32_e32 v205, v208, v205
	v_mul_f32_e32 v208, v207, v205
	v_fma_f32 v209, -v206, v208, v207
	v_fmac_f32_e32 v208, v209, v205
	v_fma_f32 v206, -v206, v208, v207
	v_div_fmas_f32 v206, v206, v205, v208
	v_div_fixup_f32 v178, v206, v204, 1.0
	v_mov_b32_e32 v164, v162
	v_mov_b32_e32 v180, v178
	s_nop 1
	v_permlane16_swap_b32_e32 v162, v164
	v_permlane16_swap_b32_e32 v178, v180
	v_mov_b32_e32 v166, v162
	v_mov_b32_e32 v168, v164
	v_mov_b32_e32 v182, v178
	v_mov_b32_e32 v184, v180
	s_nop 1
	v_permlane32_swap_b32_e32 v162, v166
	v_permlane32_swap_b32_e32 v164, v168
	v_permlane32_swap_b32_e32 v178, v182
	v_permlane32_swap_b32_e32 v180, v184
	v_pk_mul_f32 v[126:127], v[126:127], v[162:163] op_sel_hi:[1,0]
	v_pk_mul_f32 v[128:129], v[128:129], v[162:163] op_sel_hi:[1,0]
	v_pk_mul_f32 v[122:123], v[122:123], v[162:163] op_sel_hi:[1,0]
	v_pk_mul_f32 v[124:125], v[124:125], v[162:163] op_sel_hi:[1,0]
	v_pk_mul_f32 v[118:119], v[118:119], v[162:163] op_sel_hi:[1,0]
	v_pk_mul_f32 v[114:115], v[114:115], v[162:163] op_sel_hi:[1,0]
	v_pk_mul_f32 v[120:121], v[120:121], v[162:163] op_sel_hi:[1,0]
	v_pk_mul_f32 v[116:117], v[116:117], v[162:163] op_sel_hi:[1,0]
	v_pk_mul_f32 v[204:205], v[126:127], v[196:197] op_sel_hi:[1,0]
	v_pk_mul_f32 v[206:207], v[128:129], v[196:197] op_sel_hi:[1,0]
	v_pk_mul_f32 v[208:209], v[118:119], v[196:197] op_sel_hi:[1,0]
	v_pk_mul_f32 v[210:211], v[120:121], v[196:197] op_sel_hi:[1,0]
	v_exp_f32_e32 v204, v204
	v_exp_f32_e32 v205, v205
	v_exp_f32_e32 v206, v206
	v_exp_f32_e32 v207, v207
	v_exp_f32_e32 v208, v208
	v_exp_f32_e32 v209, v209
	v_exp_f32_e32 v210, v210
	v_exp_f32_e32 v211, v211
	v_pk_add_f32 v[204:205], v[204:205], 1.0 op_sel_hi:[1,0]
	v_pk_add_f32 v[206:207], v[206:207], 1.0 op_sel_hi:[1,0]
	v_pk_add_f32 v[208:209], v[208:209], 1.0 op_sel_hi:[1,0]
	v_pk_add_f32 v[210:211], v[210:211], 1.0 op_sel_hi:[1,0]
	v_rcp_f32_e32 v212, v204
	v_rcp_f32_e32 v213, v205
	v_rcp_f32_e32 v214, v206
	v_rcp_f32_e32 v215, v207
	v_rcp_f32_e32 v216, v208
	v_rcp_f32_e32 v217, v209
	v_rcp_f32_e32 v218, v210
	v_rcp_f32_e32 v219, v211
	v_pk_mul_f32 v[126:127], v[126:127], v[212:213]
	v_pk_mul_f32 v[128:129], v[128:129], v[214:215]
	v_pk_mul_f32 v[118:119], v[118:119], v[216:217]
	v_pk_mul_f32 v[120:121], v[120:121], v[218:219]
	v_pk_mul_f32 v[122:123], v[122:123], v[126:127]
	v_pk_mul_f32 v[124:125], v[124:125], v[128:129]
	v_pk_mul_f32 v[114:115], v[114:115], v[118:119]
	v_pk_mul_f32 v[116:117], v[116:117], v[120:121]
	v_cvt_pk_bf16_f32 v118, v122, v123
	v_cvt_pk_bf16_f32 v119, v124, v125
	v_cvt_pk_bf16_f32 v114, v114, v115
	v_cvt_pk_bf16_f32 v115, v116, v117
	global_store_dwordx2 v161, v[118:119], s[22:23]
	global_store_dwordx2 v161, v[114:115], s[22:23] offset:128
	v_add_u32_e32 v220, 0x16000, v161
; DI unsigned pk2(float lo, float hi) { const f32x2 v = {lo, hi}; const bf16x2_t b = __builtin_convertvector(v, bf16x2_t); return __builtin_bit_cast(unsigned, b); }
; DI float sigmoidf_(float x) { return __builtin_amdgcn_rcpf(1.0f + __expf(-x)); }
;     DI void operator()(const Acc& acc, const Unit& u, int wr, int wc, int fr, int fq) const {
;     ...
;                 for (int bj = 0; bj < 2; ++bj) {
;                     const int f0 = u.pn * 128 + bj * 64 + wc * 16 + 4 * fq;
;                     const f32x4 g = acc[ai][bj][m][0] * rr, up = acc[ai][bj][m][1] * rr;
;                     float o[4];
; #pragma unroll
;                     for (int i = 0; i < 4; ++i) o[i] = g[i] * sigmoidf_(g[i]) * up[i];
;                     u32x2 w; w.x = pk2(o[0], o[1]); w.y = pk2(o[2], o[3]);
;                     *(u32x2*)(ACT + (size_t)r * DFF + f0) = w;
	v_pk_mul_f32 v[110:111], v[110:111], v[164:165] op_sel_hi:[1,0]
	v_pk_mul_f32 v[112:113], v[112:113], v[164:165] op_sel_hi:[1,0]
	v_pk_mul_f32 v[106:107], v[106:107], v[164:165] op_sel_hi:[1,0]
	v_pk_mul_f32 v[108:109], v[108:109], v[164:165] op_sel_hi:[1,0]
	v_pk_mul_f32 v[102:103], v[102:103], v[164:165] op_sel_hi:[1,0]
	v_pk_mul_f32 v[98:99], v[98:99], v[164:165] op_sel_hi:[1,0]
	v_pk_mul_f32 v[104:105], v[104:105], v[164:165] op_sel_hi:[1,0]
	v_pk_mul_f32 v[100:101], v[100:101], v[164:165] op_sel_hi:[1,0]
	v_pk_mul_f32 v[204:205], v[110:111], v[196:197] op_sel_hi:[1,0]
	v_pk_mul_f32 v[206:207], v[112:113], v[196:197] op_sel_hi:[1,0]
	v_pk_mul_f32 v[208:209], v[102:103], v[196:197] op_sel_hi:[1,0]
	v_pk_mul_f32 v[210:211], v[104:105], v[196:197] op_sel_hi:[1,0]
	v_exp_f32_e32 v204, v204
	v_exp_f32_e32 v205, v205
	v_exp_f32_e32 v206, v206
	v_exp_f32_e32 v207, v207
	v_exp_f32_e32 v208, v208
	v_exp_f32_e32 v209, v209
	v_exp_f32_e32 v210, v210
	v_exp_f32_e32 v211, v211
	v_pk_add_f32 v[204:205], v[204:205], 1.0 op_sel_hi:[1,0]
	v_pk_add_f32 v[206:207], v[206:207], 1.0 op_sel_hi:[1,0]
	v_pk_add_f32 v[208:209], v[208:209], 1.0 op_sel_hi:[1,0]
	v_pk_add_f32 v[210:211], v[210:211], 1.0 op_sel_hi:[1,0]
	v_rcp_f32_e32 v212, v204
	v_rcp_f32_e32 v213, v205
	v_rcp_f32_e32 v214, v206
	v_rcp_f32_e32 v215, v207
	v_rcp_f32_e32 v216, v208
	v_rcp_f32_e32 v217, v209
	v_rcp_f32_e32 v218, v210
	v_rcp_f32_e32 v219, v211
	v_pk_mul_f32 v[110:111], v[110:111], v[212:213]
	v_pk_mul_f32 v[112:113], v[112:113], v[214:215]
	v_pk_mul_f32 v[102:103], v[102:103], v[216:217]
	v_pk_mul_f32 v[104:105], v[104:105], v[218:219]
	v_pk_mul_f32 v[106:107], v[106:107], v[110:111]
	v_pk_mul_f32 v[108:109], v[108:109], v[112:113]
	v_pk_mul_f32 v[98:99], v[98:99], v[102:103]
	v_pk_mul_f32 v[100:101], v[100:101], v[104:105]
	v_cvt_pk_bf16_f32 v102, v106, v107
	v_cvt_pk_bf16_f32 v103, v108, v109
	v_cvt_pk_bf16_f32 v98, v98, v99
	v_cvt_pk_bf16_f32 v99, v100, v101
	global_store_dwordx2 v220, v[102:103], s[22:23]
	global_store_dwordx2 v220, v[98:99], s[22:23] offset:128
	v_add_u32_e32 v220, 0x2c000, v161
	v_pk_mul_f32 v[94:95], v[94:95], v[166:167] op_sel_hi:[1,0]
	v_pk_mul_f32 v[96:97], v[96:97], v[166:167] op_sel_hi:[1,0]
	v_pk_mul_f32 v[90:91], v[90:91], v[166:167] op_sel_hi:[1,0]
	v_pk_mul_f32 v[92:93], v[92:93], v[166:167] op_sel_hi:[1,0]
	v_pk_mul_f32 v[86:87], v[86:87], v[166:167] op_sel_hi:[1,0]
	v_pk_mul_f32 v[82:83], v[82:83], v[166:167] op_sel_hi:[1,0]
	v_pk_mul_f32 v[88:89], v[88:89], v[166:167] op_sel_hi:[1,0]
	v_pk_mul_f32 v[84:85], v[84:85], v[166:167] op_sel_hi:[1,0]
	v_pk_mul_f32 v[204:205], v[94:95], v[196:197] op_sel_hi:[1,0]
	v_pk_mul_f32 v[206:207], v[96:97], v[196:197] op_sel_hi:[1,0]
	v_pk_mul_f32 v[208:209], v[86:87], v[196:197] op_sel_hi:[1,0]
	v_pk_mul_f32 v[210:211], v[88:89], v[196:197] op_sel_hi:[1,0]
	v_exp_f32_e32 v204, v204
	v_exp_f32_e32 v205, v205
	v_exp_f32_e32 v206, v206
	v_exp_f32_e32 v207, v207
	v_exp_f32_e32 v208, v208
	v_exp_f32_e32 v209, v209
	v_exp_f32_e32 v210, v210
	v_exp_f32_e32 v211, v211
	v_pk_add_f32 v[204:205], v[204:205], 1.0 op_sel_hi:[1,0]
	v_pk_add_f32 v[206:207], v[206:207], 1.0 op_sel_hi:[1,0]
	v_pk_add_f32 v[208:209], v[208:209], 1.0 op_sel_hi:[1,0]
	v_pk_add_f32 v[210:211], v[210:211], 1.0 op_sel_hi:[1,0]
	v_rcp_f32_e32 v212, v204
	v_rcp_f32_e32 v213, v205
	v_rcp_f32_e32 v214, v206
	v_rcp_f32_e32 v215, v207
	v_rcp_f32_e32 v216, v208
	v_rcp_f32_e32 v217, v209
	v_rcp_f32_e32 v218, v210
	v_rcp_f32_e32 v219, v211
	v_pk_mul_f32 v[94:95], v[94:95], v[212:213]
	v_pk_mul_f32 v[96:97], v[96:97], v[214:215]
	v_pk_mul_f32 v[86:87], v[86:87], v[216:217]
	v_pk_mul_f32 v[88:89], v[88:89], v[218:219]
	v_pk_mul_f32 v[90:91], v[90:91], v[94:95]
	v_pk_mul_f32 v[92:93], v[92:93], v[96:97]
	v_pk_mul_f32 v[82:83], v[82:83], v[86:87]
	v_pk_mul_f32 v[84:85], v[84:85], v[88:89]
	v_cvt_pk_bf16_f32 v86, v90, v91
	v_cvt_pk_bf16_f32 v87, v92, v93
	v_cvt_pk_bf16_f32 v82, v82, v83
	v_cvt_pk_bf16_f32 v83, v84, v85
	global_store_dwordx2 v220, v[86:87], s[22:23]
	global_store_dwordx2 v220, v[82:83], s[22:23] offset:128
	v_add_u32_e32 v220, 0x42000, v161
	v_pk_mul_f32 v[78:79], v[78:79], v[168:169] op_sel_hi:[1,0]
	v_pk_mul_f32 v[80:81], v[80:81], v[168:169] op_sel_hi:[1,0]
	v_pk_mul_f32 v[74:75], v[74:75], v[168:169] op_sel_hi:[1,0]
	v_pk_mul_f32 v[76:77], v[76:77], v[168:169] op_sel_hi:[1,0]
	v_pk_mul_f32 v[70:71], v[70:71], v[168:169] op_sel_hi:[1,0]
	v_pk_mul_f32 v[66:67], v[66:67], v[168:169] op_sel_hi:[1,0]
	v_pk_mul_f32 v[72:73], v[72:73], v[168:169] op_sel_hi:[1,0]
	v_pk_mul_f32 v[68:69], v[68:69], v[168:169] op_sel_hi:[1,0]
	v_pk_mul_f32 v[204:205], v[78:79], v[196:197] op_sel_hi:[1,0]
	v_pk_mul_f32 v[206:207], v[80:81], v[196:197] op_sel_hi:[1,0]
	v_pk_mul_f32 v[208:209], v[70:71], v[196:197] op_sel_hi:[1,0]
	v_pk_mul_f32 v[210:211], v[72:73], v[196:197] op_sel_hi:[1,0]
	v_exp_f32_e32 v204, v204
	v_exp_f32_e32 v205, v205
	v_exp_f32_e32 v206, v206
	v_exp_f32_e32 v207, v207
	v_exp_f32_e32 v208, v208
	v_exp_f32_e32 v209, v209
	v_exp_f32_e32 v210, v210
	v_exp_f32_e32 v211, v211
	v_pk_add_f32 v[204:205], v[204:205], 1.0 op_sel_hi:[1,0]
	v_pk_add_f32 v[206:207], v[206:207], 1.0 op_sel_hi:[1,0]
	v_pk_add_f32 v[208:209], v[208:209], 1.0 op_sel_hi:[1,0]
	v_pk_add_f32 v[210:211], v[210:211], 1.0 op_sel_hi:[1,0]
	v_rcp_f32_e32 v212, v204
	v_rcp_f32_e32 v213, v205
	v_rcp_f32_e32 v214, v206
	v_rcp_f32_e32 v215, v207
	v_rcp_f32_e32 v216, v208
	v_rcp_f32_e32 v217, v209
	v_rcp_f32_e32 v218, v210
	v_rcp_f32_e32 v219, v211
	v_pk_mul_f32 v[78:79], v[78:79], v[212:213]
	v_pk_mul_f32 v[80:81], v[80:81], v[214:215]
	v_pk_mul_f32 v[70:71], v[70:71], v[216:217]
; DI unsigned pk2(float lo, float hi) { const f32x2 v = {lo, hi}; const bf16x2_t b = __builtin_convertvector(v, bf16x2_t); return __builtin_bit_cast(unsigned, b); }
; DI float sigmoidf_(float x) { return __builtin_amdgcn_rcpf(1.0f + __expf(-x)); }
;     DI void operator()(const Acc& acc, const Unit& u, int wr, int wc, int fr, int fq) const {
;     ...
;                 for (int bj = 0; bj < 2; ++bj) {
;                     const int f0 = u.pn * 128 + bj * 64 + wc * 16 + 4 * fq;
;                     const f32x4 g = acc[ai][bj][m][0] * rr, up = acc[ai][bj][m][1] * rr;
;                     float o[4];
; #pragma unroll
;                     for (int i = 0; i < 4; ++i) o[i] = g[i] * sigmoidf_(g[i]) * up[i];
;                     u32x2 w; w.x = pk2(o[0], o[1]); w.y = pk2(o[2], o[3]);
;                     *(u32x2*)(ACT + (size_t)r * DFF + f0) = w;
	v_pk_mul_f32 v[72:73], v[72:73], v[218:219]
	v_pk_mul_f32 v[74:75], v[74:75], v[78:79]
	v_pk_mul_f32 v[76:77], v[76:77], v[80:81]
	v_pk_mul_f32 v[66:67], v[66:67], v[70:71]
	v_pk_mul_f32 v[68:69], v[68:69], v[72:73]
	v_cvt_pk_bf16_f32 v70, v74, v75
	v_cvt_pk_bf16_f32 v71, v76, v77
	v_cvt_pk_bf16_f32 v66, v66, v67
	v_cvt_pk_bf16_f32 v67, v68, v69
	global_store_dwordx2 v220, v[70:71], s[22:23]
	global_store_dwordx2 v220, v[66:67], s[22:23] offset:128
	v_add_u32_e32 v220, 0xb0000, v161
	v_pk_mul_f32 v[62:63], v[62:63], v[178:179] op_sel_hi:[1,0]
	v_pk_mul_f32 v[64:65], v[64:65], v[178:179] op_sel_hi:[1,0]
	v_pk_mul_f32 v[58:59], v[58:59], v[178:179] op_sel_hi:[1,0]
	v_pk_mul_f32 v[60:61], v[60:61], v[178:179] op_sel_hi:[1,0]
	v_pk_mul_f32 v[54:55], v[54:55], v[178:179] op_sel_hi:[1,0]
	v_pk_mul_f32 v[50:51], v[50:51], v[178:179] op_sel_hi:[1,0]
	v_pk_mul_f32 v[56:57], v[56:57], v[178:179] op_sel_hi:[1,0]
	v_pk_mul_f32 v[52:53], v[52:53], v[178:179] op_sel_hi:[1,0]
	v_pk_mul_f32 v[204:205], v[62:63], v[196:197] op_sel_hi:[1,0]
	v_pk_mul_f32 v[206:207], v[64:65], v[196:197] op_sel_hi:[1,0]
	v_pk_mul_f32 v[208:209], v[54:55], v[196:197] op_sel_hi:[1,0]
	v_pk_mul_f32 v[210:211], v[56:57], v[196:197] op_sel_hi:[1,0]
	v_exp_f32_e32 v204, v204
	v_exp_f32_e32 v205, v205
	v_exp_f32_e32 v206, v206
	v_exp_f32_e32 v207, v207
	v_exp_f32_e32 v208, v208
	v_exp_f32_e32 v209, v209
	v_exp_f32_e32 v210, v210
	v_exp_f32_e32 v211, v211
	v_pk_add_f32 v[204:205], v[204:205], 1.0 op_sel_hi:[1,0]
	v_pk_add_f32 v[206:207], v[206:207], 1.0 op_sel_hi:[1,0]
	v_pk_add_f32 v[208:209], v[208:209], 1.0 op_sel_hi:[1,0]
	v_pk_add_f32 v[210:211], v[210:211], 1.0 op_sel_hi:[1,0]
	v_rcp_f32_e32 v212, v204
	v_rcp_f32_e32 v213, v205
	v_rcp_f32_e32 v214, v206
	v_rcp_f32_e32 v215, v207
	v_rcp_f32_e32 v216, v208
	v_rcp_f32_e32 v217, v209
	v_rcp_f32_e32 v218, v210
	v_rcp_f32_e32 v219, v211
	v_pk_mul_f32 v[62:63], v[62:63], v[212:213]
	v_pk_mul_f32 v[64:65], v[64:65], v[214:215]
	v_pk_mul_f32 v[54:55], v[54:55], v[216:217]
	v_pk_mul_f32 v[56:57], v[56:57], v[218:219]
	v_pk_mul_f32 v[58:59], v[58:59], v[62:63]
	v_pk_mul_f32 v[60:61], v[60:61], v[64:65]
	v_pk_mul_f32 v[50:51], v[50:51], v[54:55]
	v_pk_mul_f32 v[52:53], v[52:53], v[56:57]
	v_cvt_pk_bf16_f32 v54, v58, v59
	v_cvt_pk_bf16_f32 v55, v60, v61
	v_cvt_pk_bf16_f32 v50, v50, v51
	v_cvt_pk_bf16_f32 v51, v52, v53
	global_store_dwordx2 v220, v[54:55], s[22:23]
	global_store_dwordx2 v220, v[50:51], s[22:23] offset:128
	v_add_u32_e32 v220, 0xc6000, v161
	v_pk_mul_f32 v[46:47], v[46:47], v[180:181] op_sel_hi:[1,0]
	v_pk_mul_f32 v[48:49], v[48:49], v[180:181] op_sel_hi:[1,0]
	v_pk_mul_f32 v[42:43], v[42:43], v[180:181] op_sel_hi:[1,0]
	v_pk_mul_f32 v[44:45], v[44:45], v[180:181] op_sel_hi:[1,0]
	v_pk_mul_f32 v[38:39], v[38:39], v[180:181] op_sel_hi:[1,0]
	v_pk_mul_f32 v[34:35], v[34:35], v[180:181] op_sel_hi:[1,0]
	v_pk_mul_f32 v[40:41], v[40:41], v[180:181] op_sel_hi:[1,0]
	v_pk_mul_f32 v[36:37], v[36:37], v[180:181] op_sel_hi:[1,0]
	v_pk_mul_f32 v[204:205], v[46:47], v[196:197] op_sel_hi:[1,0]
	v_pk_mul_f32 v[206:207], v[48:49], v[196:197] op_sel_hi:[1,0]
	v_pk_mul_f32 v[208:209], v[38:39], v[196:197] op_sel_hi:[1,0]
	v_pk_mul_f32 v[210:211], v[40:41], v[196:197] op_sel_hi:[1,0]
	v_exp_f32_e32 v204, v204
	v_exp_f32_e32 v205, v205
	v_exp_f32_e32 v206, v206
	v_exp_f32_e32 v207, v207
	v_exp_f32_e32 v208, v208
	v_exp_f32_e32 v209, v209
	v_exp_f32_e32 v210, v210
	v_exp_f32_e32 v211, v211
	v_pk_add_f32 v[204:205], v[204:205], 1.0 op_sel_hi:[1,0]
	v_pk_add_f32 v[206:207], v[206:207], 1.0 op_sel_hi:[1,0]
	v_pk_add_f32 v[208:209], v[208:209], 1.0 op_sel_hi:[1,0]
	v_pk_add_f32 v[210:211], v[210:211], 1.0 op_sel_hi:[1,0]
	v_rcp_f32_e32 v212, v204
	v_rcp_f32_e32 v213, v205
	v_rcp_f32_e32 v214, v206
	v_rcp_f32_e32 v215, v207
	v_rcp_f32_e32 v216, v208
	v_rcp_f32_e32 v217, v209
	v_rcp_f32_e32 v218, v210
	v_rcp_f32_e32 v219, v211
	v_pk_mul_f32 v[46:47], v[46:47], v[212:213]
	v_pk_mul_f32 v[48:49], v[48:49], v[214:215]
	v_pk_mul_f32 v[38:39], v[38:39], v[216:217]
	v_pk_mul_f32 v[40:41], v[40:41], v[218:219]
	v_pk_mul_f32 v[42:43], v[42:43], v[46:47]
	v_pk_mul_f32 v[44:45], v[44:45], v[48:49]
	v_pk_mul_f32 v[34:35], v[34:35], v[38:39]
	v_pk_mul_f32 v[36:37], v[36:37], v[40:41]
	v_cvt_pk_bf16_f32 v38, v42, v43
	v_cvt_pk_bf16_f32 v39, v44, v45
; DI unsigned pk2(float lo, float hi) { const f32x2 v = {lo, hi}; const bf16x2_t b = __builtin_convertvector(v, bf16x2_t); return __builtin_bit_cast(unsigned, b); }
; DI float sigmoidf_(float x) { return __builtin_amdgcn_rcpf(1.0f + __expf(-x)); }
;     DI void operator()(const Acc& acc, const Unit& u, int wr, int wc, int fr, int fq) const {
;     ...
;                 for (int bj = 0; bj < 2; ++bj) {
;                     const int f0 = u.pn * 128 + bj * 64 + wc * 16 + 4 * fq;
;                     const f32x4 g = acc[ai][bj][m][0] * rr, up = acc[ai][bj][m][1] * rr;
;                     float o[4];
; #pragma unroll
;                     for (int i = 0; i < 4; ++i) o[i] = g[i] * sigmoidf_(g[i]) * up[i];
;                     u32x2 w; w.x = pk2(o[0], o[1]); w.y = pk2(o[2], o[3]);
;                     *(u32x2*)(ACT + (size_t)r * DFF + f0) = w;
;                 }
;             }
;     }
	v_cvt_pk_bf16_f32 v34, v34, v35
	v_cvt_pk_bf16_f32 v35, v36, v37
	global_store_dwordx2 v220, v[38:39], s[22:23]
	global_store_dwordx2 v220, v[34:35], s[22:23] offset:128
	v_add_u32_e32 v220, 0xdc000, v161
	v_pk_mul_f32 v[30:31], v[30:31], v[182:183] op_sel_hi:[1,0]
	v_pk_mul_f32 v[32:33], v[32:33], v[182:183] op_sel_hi:[1,0]
	v_pk_mul_f32 v[26:27], v[26:27], v[182:183] op_sel_hi:[1,0]
	v_pk_mul_f32 v[28:29], v[28:29], v[182:183] op_sel_hi:[1,0]
	v_pk_mul_f32 v[22:23], v[22:23], v[182:183] op_sel_hi:[1,0]
	v_pk_mul_f32 v[18:19], v[18:19], v[182:183] op_sel_hi:[1,0]
	v_pk_mul_f32 v[24:25], v[24:25], v[182:183] op_sel_hi:[1,0]
	v_pk_mul_f32 v[20:21], v[20:21], v[182:183] op_sel_hi:[1,0]
	v_pk_mul_f32 v[204:205], v[30:31], v[196:197] op_sel_hi:[1,0]
	v_pk_mul_f32 v[206:207], v[32:33], v[196:197] op_sel_hi:[1,0]
	v_pk_mul_f32 v[208:209], v[22:23], v[196:197] op_sel_hi:[1,0]
	v_pk_mul_f32 v[210:211], v[24:25], v[196:197] op_sel_hi:[1,0]
	v_exp_f32_e32 v204, v204
	v_exp_f32_e32 v205, v205
	v_exp_f32_e32 v206, v206
	v_exp_f32_e32 v207, v207
	v_exp_f32_e32 v208, v208
	v_exp_f32_e32 v209, v209
	v_exp_f32_e32 v210, v210
	v_exp_f32_e32 v211, v211
	v_pk_add_f32 v[204:205], v[204:205], 1.0 op_sel_hi:[1,0]
	v_pk_add_f32 v[206:207], v[206:207], 1.0 op_sel_hi:[1,0]
	v_pk_add_f32 v[208:209], v[208:209], 1.0 op_sel_hi:[1,0]
	v_pk_add_f32 v[210:211], v[210:211], 1.0 op_sel_hi:[1,0]
	v_rcp_f32_e32 v212, v204
	v_rcp_f32_e32 v213, v205
	v_rcp_f32_e32 v214, v206
	v_rcp_f32_e32 v215, v207
	v_rcp_f32_e32 v216, v208
	v_rcp_f32_e32 v217, v209
	v_rcp_f32_e32 v218, v210
	v_rcp_f32_e32 v219, v211
	v_pk_mul_f32 v[30:31], v[30:31], v[212:213]
	v_pk_mul_f32 v[32:33], v[32:33], v[214:215]
	v_pk_mul_f32 v[22:23], v[22:23], v[216:217]
	v_pk_mul_f32 v[24:25], v[24:25], v[218:219]
	v_pk_mul_f32 v[26:27], v[26:27], v[30:31]
	v_pk_mul_f32 v[28:29], v[28:29], v[32:33]
	v_pk_mul_f32 v[18:19], v[18:19], v[22:23]
	v_pk_mul_f32 v[20:21], v[20:21], v[24:25]
	v_cvt_pk_bf16_f32 v22, v26, v27
	v_cvt_pk_bf16_f32 v23, v28, v29
	v_cvt_pk_bf16_f32 v18, v18, v19
	v_cvt_pk_bf16_f32 v19, v20, v21
	global_store_dwordx2 v220, v[22:23], s[22:23]
	global_store_dwordx2 v220, v[18:19], s[22:23] offset:128
	v_add_u32_e32 v220, 0xf2000, v161
	v_pk_mul_f32 v[14:15], v[14:15], v[184:185] op_sel_hi:[1,0]
	v_pk_mul_f32 v[16:17], v[16:17], v[184:185] op_sel_hi:[1,0]
	v_pk_mul_f32 v[10:11], v[10:11], v[184:185] op_sel_hi:[1,0]
	v_pk_mul_f32 v[12:13], v[12:13], v[184:185] op_sel_hi:[1,0]
	v_pk_mul_f32 v[6:7], v[6:7], v[184:185] op_sel_hi:[1,0]
	v_pk_mul_f32 v[2:3], v[2:3], v[184:185] op_sel_hi:[1,0]
	v_pk_mul_f32 v[8:9], v[8:9], v[184:185] op_sel_hi:[1,0]
	v_pk_mul_f32 v[4:5], v[4:5], v[184:185] op_sel_hi:[1,0]
	v_pk_mul_f32 v[204:205], v[14:15], v[196:197] op_sel_hi:[1,0]
	v_pk_mul_f32 v[206:207], v[16:17], v[196:197] op_sel_hi:[1,0]
	v_pk_mul_f32 v[208:209], v[6:7], v[196:197] op_sel_hi:[1,0]
	v_pk_mul_f32 v[210:211], v[8:9], v[196:197] op_sel_hi:[1,0]
	v_exp_f32_e32 v204, v204
	v_exp_f32_e32 v205, v205
	v_exp_f32_e32 v206, v206
	v_exp_f32_e32 v207, v207
	v_exp_f32_e32 v208, v208
	v_exp_f32_e32 v209, v209
	v_exp_f32_e32 v210, v210
	v_exp_f32_e32 v211, v211
	v_pk_add_f32 v[204:205], v[204:205], 1.0 op_sel_hi:[1,0]
	v_pk_add_f32 v[206:207], v[206:207], 1.0 op_sel_hi:[1,0]
	v_pk_add_f32 v[208:209], v[208:209], 1.0 op_sel_hi:[1,0]
	v_pk_add_f32 v[210:211], v[210:211], 1.0 op_sel_hi:[1,0]
	v_rcp_f32_e32 v212, v204
	v_rcp_f32_e32 v213, v205
	v_rcp_f32_e32 v214, v206
	v_rcp_f32_e32 v215, v207
	v_rcp_f32_e32 v216, v208
	v_rcp_f32_e32 v217, v209
	v_rcp_f32_e32 v218, v210
	v_rcp_f32_e32 v219, v211
	v_pk_mul_f32 v[14:15], v[14:15], v[212:213]
	v_pk_mul_f32 v[16:17], v[16:17], v[214:215]
	v_pk_mul_f32 v[6:7], v[6:7], v[216:217]
	v_pk_mul_f32 v[8:9], v[8:9], v[218:219]
	v_pk_mul_f32 v[10:11], v[10:11], v[14:15]
	v_pk_mul_f32 v[12:13], v[12:13], v[16:17]
	v_pk_mul_f32 v[2:3], v[2:3], v[6:7]
	v_pk_mul_f32 v[4:5], v[4:5], v[8:9]
	v_cvt_pk_bf16_f32 v6, v10, v11
	v_cvt_pk_bf16_f32 v7, v12, v13
	v_cvt_pk_bf16_f32 v2, v2, v3
	v_cvt_pk_bf16_f32 v3, v4, v5
	global_store_dwordx2 v220, v[6:7], s[22:23]
	global_store_dwordx2 v220, v[2:3], s[22:23] offset:128
	s_andn2_b64 vcc, exec, s[4:5]
	s_mov_b64 s[4:5], -1
	s_cbranch_vccnz .LBB0_1030
	s_andn2_b64 vcc, exec, s[10:11]
	s_cbranch_vccnz .LBB0_1029
	s_barrier
	s_branch .LBB0_1029
